# P0: ffn2/w_in/w_out weight transposes moved into idle third round of down GEMM 1; adaLN workgroups skip transposes
# speedup vs baseline: 1.0076x; 1.0076x over previous
; #define LAS __attribute__((address_space(3)))
; DI void p0_prologue(const Args& a, LAS unsigned char* lds, int tid, int wave, int lane, bool first) {
;     ...
;     LAS float* scr = (LAS float*)(lds + wave * 16384);
;     const int gw = blockIdx.x * 8 + wave, NGW = gridDim.x * 8;
;     constexpr int I_UP = (D / 64) * (NUP / 32), I_DN = (FF / 64) * (D / 32), I_IN = (D / 64) * (NIN / 32), I_OUT = (D / 64) * (D / 32);
;     constexpr int NITEMS = 2 * I_UP + 2 * I_DN + I_IN + I_OUT;
;     for (int it = gw; it < NITEMS; it += NGW) {
;         int r = it;
;         if (r < 2 * I_UP) { const int which = r >= I_UP; r -= which * I_UP; const int nb = r % (NUP / 32), kb = r / (NUP / 32);
;             p0_transpose_item(a.in[which ? 18 : 12], D, NUP, srccol_up(32 * nb), (bf16_t*)(ws + (which ? WS_WUP2 : WS_WUP1)), 32 * nb, 64 * kb, scr, lane); continue; }
;         r -= 2 * I_UP;
;         if (r < 2 * I_DN) { const int which = r >= I_DN; r -= which * I_DN; const int nb = r % (D / 32), kb = r / (D / 32);
;             p0_transpose_item(a.in[which ? 19 : 13], FF, D, 32 * nb, (bf16_t*)(ws + (which ? WS_WDN2 : WS_WDN1)), 32 * nb, 64 * kb, scr, lane); continue; }
;         r -= 2 * I_DN;
;         if (r < I_IN) { const int nb = r % (NIN / 32), kb = r / (NIN / 32);
;             p0_transpose_item(a.in[14], D, NIN, srccol_in(32 * nb), (bf16_t*)(ws + WS_WIN), 32 * nb, 64 * kb, scr, lane); continue; }
;         r -= I_IN;
;         { const int nb = r % (D / 32), kb = r / (D / 32);
;             p0_transpose_item(a.in[17], D, D, 32 * nb, (bf16_t*)(ws + WS_WOUT), 32 * nb, 64 * kb, scr, lane); }
;     }
.LBB0_648:
	s_cmp_lg_u32 s77, 3
	s_cbranch_scc1 .Lno_tail
	v_readlane_b32 s92, v255, 31
	v_readlane_b32 s4, v255, 18
	s_cmpk_lg_i32 s92, 0x100
	s_cbranch_scc1 .Lno_tail
	s_cmp_lt_u32 s4, 32
	s_cbranch_scc1 .Lno_tail
	v_readlane_b32 s8, v255, 49
	s_lshl_b32 s4, s4, 3
	s_add_i32 s100, s4, s8
	s_addk_i32 s100, 0xff00
	s_movk_i32 s101, 0x700
	s_waitcnt vmcnt(0) lgkmcnt(0)
	v_mov_b32_e32 v172, v194
	v_mov_b32_e32 v161, 0
	v_and_b32_e32 v207, 63, v172
	v_readlane_b32 s34, v255, 43
	v_readlane_b32 s38, v255, 21
	v_readlane_b32 s39, v255, 22
	v_readlane_b32 s40, v255, 23
	v_readlane_b32 s41, v255, 24
	v_readlane_b32 s42, v255, 25
	v_readlane_b32 s43, v255, 26
	v_readlane_b32 s90, v255, 29
	v_readlane_b32 s91, v255, 30
	s_mov_b32 s36, 0x800000
	s_mov_b32 s53, 0
	s_movk_i32 s79, 0x84
	s_movk_i32 s73, 0x3800
	s_movk_i32 s76, 0x5800
	s_branch .Ltr_setup

; DI void ada_item(int it, const float* cP, const float* cS, const float* wada, const float* bada, float* mod, LAS float* red, int tid, int wave, int lane) {
;     ...
;     for (int u = 0; u < 2; ++u) {
;         const int kb = 128 * wave + 64 * u;
; #pragma unroll 4
;         for (int b = 0; b < 36; ++b) { const float cv = b < 4 ? cP[b * 1024 + kb + lane] : cS[(b - 4) * 1024 + kb + lane]; cs[lane * 36 + b] = cv / (1.f + __expf(-cv)); }
;         asm volatile("s_waitcnt lgkmcnt(0)" ::: "memory");
; #pragma unroll 1
;         for (int k8 = 0; k8 < 8; ++k8) {
;             float wv[8];
; #pragma unroll
;             for (int j = 0; j < 8; ++j) wv[j] = wada[(size_t)(kb + 8 * k8 + j) * NMOD + c0 + lane];
.LBB0_706:
	s_or_b32 s13, s8, s18
	s_xor_b64 s[14:15], s[6:7], -1
	v_or_b32_e32 v36, s13, v207
	v_add_u32_e32 v37, s13, v87
	s_movk_i32 s20, 0xc00
	v_mov_b32_e32 v38, v85

; DI void p0_prologue(const Args& a, LAS unsigned char* lds, int tid, int wave, int lane, bool first) {
;     ...
;     const int gw = blockIdx.x * 8 + wave, NGW = gridDim.x * 8;
;     constexpr int I_UP = (D / 64) * (NUP / 32), I_DN = (FF / 64) * (D / 32), I_IN = (D / 64) * (NIN / 32), I_OUT = (D / 64) * (D / 32);
;     constexpr int NITEMS = 2 * I_UP + 2 * I_DN + I_IN + I_OUT;
;     for (int it = gw; it < NITEMS; it += NGW) {
;         int r = it;
;         if (r < 2 * I_UP) { const int which = r >= I_UP; r -= which * I_UP; const int nb = r % (NUP / 32), kb = r / (NUP / 32);
;             p0_transpose_item(a.in[which ? 18 : 12], D, NUP, srccol_up(32 * nb), (bf16_t*)(ws + (which ? WS_WUP2 : WS_WUP1)), 32 * nb, 64 * kb, scr, lane); continue; }
;         r -= 2 * I_UP;
;         if (r < 2 * I_DN) { const int which = r >= I_DN; r -= which * I_DN; const int nb = r % (D / 32), kb = r / (D / 32);
;             p0_transpose_item(a.in[which ? 19 : 13], FF, D, 32 * nb, (bf16_t*)(ws + (which ? WS_WDN2 : WS_WDN1)), 32 * nb, 64 * kb, scr, lane); continue; }
;         r -= 2 * I_DN;
;         if (r < I_IN) { const int nb = r % (NIN / 32), kb = r / (NIN / 32);
;             p0_transpose_item(a.in[14], D, NIN, srccol_in(32 * nb), (bf16_t*)(ws + WS_WIN), 32 * nb, 64 * kb, scr, lane); continue; }
;         r -= I_IN;
;         { const int nb = r % (D / 32), kb = r / (D / 32);
;             p0_transpose_item(a.in[17], D, D, 32 * nb, (bf16_t*)(ws + WS_WOUT), 32 * nb, 64 * kb, scr, lane); }
;     }
.LBB0_717:
	s_or_b64 exec, exec, s[4:5]
	v_readlane_b32 s8, v255, 49
	s_add_i32 s100, s8, s34
	s_mov_b32 s101, 0
	s_cmpk_lg_i32 s92, 0x100
	s_cbranch_scc1 .Ltr_setup
	s_cmpk_lt_i32 s34, 0x480
	s_cbranch_scc1 .LBB0_744
	s_addk_i32 s100, 0xfb80
	s_movk_i32 s101, 0x380
.Ltr_setup:
	v_readlane_b32 s6, v253, 16
	v_readlane_b32 s7, v253, 17
	s_load_dword s4, s[6:7], 0x10
	s_nop 0
	s_load_dword s6, s[6:7], 0x0
	v_lshlrev_b32_e32 v1, 3, v207
	v_and_b32_e32 v2, 31, v172
	v_lshrrev_b32_e32 v3, 3, v207
	s_waitcnt lgkmcnt(0)
	s_lshr_b32 s4, s4, 16
	s_cmp_lg_u32 s4, 0
	s_cselect_b64 s[4:5], -1, 0
	s_cmp_lg_u64 s[4:5], 0
	s_addc_u32 s4, s6, 0
	s_lshl_b32 s5, s8, 14
	v_and_b32_e32 v6, 56, v1
	s_lshl_b32 s11, s4, 3
	s_add_i32 s4, s5, 0
	v_lshlrev_b32_e32 v14, 2, v2
	v_mul_u32_u24_e32 v1, 0x84, v6
	v_lshlrev_b32_e32 v5, 2, v3
	v_add_u32_e32 v4, s4, v14
	v_readlane_b32 s6, v253, 59
	v_add3_u32 v5, s4, v1, v5
	v_readlane_b32 s4, v254, 49
	v_readlane_b32 s12, v253, 0
	v_lshrrev_b32_e32 v0, 5, v207
	v_lshlrev_b32_e32 v160, 1, v6
	v_readlane_b32 s7, v253, 60
	v_readlane_b32 s5, v254, 50
	v_mov_b32_e32 v15, v161
	v_readlane_b32 s24, v253, 12
	v_readlane_b32 s25, v253, 13
	v_lshl_add_u64 v[8:9], s[6:7], 0, v[160:161]
	v_or_b32_e32 v7, 8, v3
	v_or_b32_e32 v18, 16, v3
	v_or_b32_e32 v19, 24, v3
	v_lshl_add_u64 v[10:11], s[4:5], 0, v[160:161]
	v_lshl_add_u64 v[12:13], s[38:39], 0, v[14:15]
	v_lshl_add_u64 v[14:15], s[24:25], 0, v[14:15]
	v_mov_b32_e32 v1, v0
	v_readlane_b32 s13, v253, 1
	v_readlane_b32 s14, v253, 2
	v_readlane_b32 s15, v253, 3
	v_readlane_b32 s16, v253, 4
	v_readlane_b32 s17, v253, 5
	v_readlane_b32 s18, v253, 6
	v_readlane_b32 s19, v253, 7
	v_readlane_b32 s20, v253, 8
	v_readlane_b32 s21, v253, 9
	v_readlane_b32 s22, v253, 10
	v_readlane_b32 s23, v253, 11
	v_readlane_b32 s26, v253, 14
	v_readlane_b32 s27, v253, 15
	s_cmp_eq_u32 s101, 0
	s_cselect_b32 s101, s11, s101
	s_branch .Ltr_map
.LBB0_719:
	s_add_i32 s100, s100, s101
.Ltr_map:
	s_cmpk_lg_i32 s92, 0x100
	s_cbranch_scc1 .Ltr_map_any
	s_cmp_lg_u32 s77, 0
	s_cbranch_scc1 .Ltr_map_tail
	s_cmpk_gt_i32 s100, 0x107f
	s_cbranch_scc1 .LBB0_744
	s_mov_b32 s10, s100
	s_cmpk_lt_i32 s100, 0xb00
	s_cbranch_scc1 .LBB0_720
	s_addk_i32 s10, 0xb00
	s_branch .LBB0_720
.Ltr_map_tail:
	s_cmpk_gt_i32 s100, 0x197f
	s_cbranch_scc1 .LBB0_744
	s_add_i32 s10, s100, 0xb00
	s_cmpk_lt_i32 s100, 0xb00
	s_cbranch_scc1 .LBB0_720
	s_addk_i32 s10, 0x580
	s_branch .LBB0_720
.Ltr_map_any:
	s_mov_b32 s10, s100
	s_cmpk_gt_i32 s10, 0x29ff
	s_cbranch_scc1 .LBB0_744

; DI void p0_prologue(const Args& a, LAS unsigned char* lds, int tid, int wave, int lane, bool first) {
;     ...
;     for (int it = gw; it < NITEMS; it += NGW) {
;         int r = it;
;         if (r < 2 * I_UP) { const int which = r >= I_UP; r -= which * I_UP; const int nb = r % (NUP / 32), kb = r / (NUP / 32);
;             p0_transpose_item(a.in[which ? 18 : 12], D, NUP, srccol_up(32 * nb), (bf16_t*)(ws + (which ? WS_WUP2 : WS_WUP1)), 32 * nb, 64 * kb, scr, lane); continue; }
;         r -= 2 * I_UP;
;         if (r < 2 * I_DN) { const int which = r >= I_DN; r -= which * I_DN; const int nb = r % (D / 32), kb = r / (D / 32);
;             p0_transpose_item(a.in[which ? 19 : 13], FF, D, 32 * nb, (bf16_t*)(ws + (which ? WS_WDN2 : WS_WDN1)), 32 * nb, 64 * kb, scr, lane); continue; }
;         r -= 2 * I_DN;
;         if (r < I_IN) { const int nb = r % (NIN / 32), kb = r / (NIN / 32);
;             p0_transpose_item(a.in[14], D, NIN, srccol_in(32 * nb), (bf16_t*)(ws + WS_WIN), 32 * nb, 64 * kb, scr, lane); continue; }
;         r -= I_IN;
;         { const int nb = r % (D / 32), kb = r / (D / 32);
;             p0_transpose_item(a.in[17], D, D, 32 * nb, (bf16_t*)(ws + WS_WOUT), 32 * nb, 64 * kb, scr, lane); }
;     }
.LBB0_744:
	v_readlane_b32 s65, v255, 50
	v_readlane_b32 s36, v255, 19

; __global__ void __launch_bounds__(512, 2) fwd(Args a) {
	.amdhsa_kernel _ZN2mk3fwdENS_4ArgsE
		.amdhsa_group_segment_fixed_size 0
		.amdhsa_private_segment_fixed_size 0
		.amdhsa_kernarg_size 432
		.amdhsa_user_sgpr_count 2
		.amdhsa_user_sgpr_dispatch_ptr 0
		.amdhsa_user_sgpr_queue_ptr 0
		.amdhsa_user_sgpr_kernarg_segment_ptr 1
		.amdhsa_user_sgpr_dispatch_id 0
		.amdhsa_user_sgpr_kernarg_preload_length 0
		.amdhsa_user_sgpr_kernarg_preload_offset 0
		.amdhsa_user_sgpr_private_segment_size 0
		.amdhsa_uses_dynamic_stack 0
		.amdhsa_enable_private_segment 0
		.amdhsa_system_sgpr_workgroup_id_x 1
		.amdhsa_system_sgpr_workgroup_id_y 0
		.amdhsa_system_sgpr_workgroup_id_z 0
		.amdhsa_system_sgpr_workgroup_info 0
		.amdhsa_system_vgpr_workitem_id 2
		.amdhsa_next_free_vgpr 256
		.amdhsa_next_free_sgpr 102
		.amdhsa_accum_offset 256
		.amdhsa_reserve_vcc 1
		.amdhsa_float_round_mode_32 0
		.amdhsa_float_round_mode_16_64 0
		.amdhsa_float_denorm_mode_32 3
		.amdhsa_float_denorm_mode_16_64 3
		.amdhsa_dx10_clamp 1
		.amdhsa_ieee_mode 1
		.amdhsa_fp16_overflow 0
		.amdhsa_tg_split 0
		.amdhsa_exception_fp_ieee_invalid_op 0
		.amdhsa_exception_fp_denorm_src 0
		.amdhsa_exception_fp_ieee_div_zero 0
		.amdhsa_exception_fp_ieee_overflow 0
		.amdhsa_exception_fp_ieee_underflow 0
		.amdhsa_exception_fp_ieee_inexact 0
		.amdhsa_exception_int_div_zero 0
	.end_amdhsa_kernel

; __global__ void __launch_bounds__(512, 2) fwd(Args a) {
.Lfunc_end0:
	.size	_ZN2mk3fwdENS_4ArgsE, .Lfunc_end0-_ZN2mk3fwdENS_4ArgsE
	.set _ZN2mk3fwdENS_4ArgsE.num_vgpr, 256
	.set _ZN2mk3fwdENS_4ArgsE.num_agpr, 0
	.set _ZN2mk3fwdENS_4ArgsE.numbered_sgpr, 102
	.set _ZN2mk3fwdENS_4ArgsE.num_named_barrier, 0
	.set _ZN2mk3fwdENS_4ArgsE.private_seg_size, 0
	.set _ZN2mk3fwdENS_4ArgsE.uses_vcc, 1
	.set _ZN2mk3fwdENS_4ArgsE.uses_flat_scratch, 0
	.set _ZN2mk3fwdENS_4ArgsE.has_dyn_sized_stack, 0
	.set _ZN2mk3fwdENS_4ArgsE.has_recursion, 0
	.set _ZN2mk3fwdENS_4ArgsE.has_indirect_call, 0

; __global__ void __launch_bounds__(512, 2) fwd(Args a) {
amdhsa.kernels:
  - .agpr_count:     0
    .args:
      - .offset:         0
        .size:           176
        .value_kind:     by_value
      - .offset:         176
        .size:           4
        .value_kind:     hidden_block_count_x
      - .offset:         180
        .size:           4
        .value_kind:     hidden_block_count_y
      - .offset:         184
        .size:           4
        .value_kind:     hidden_block_count_z
      - .offset:         188
        .size:           2
        .value_kind:     hidden_group_size_x
      - .offset:         190
        .size:           2
        .value_kind:     hidden_group_size_y
      - .offset:         192
        .size:           2
        .value_kind:     hidden_group_size_z
      - .offset:         194
        .size:           2
        .value_kind:     hidden_remainder_x
      - .offset:         196
        .size:           2
        .value_kind:     hidden_remainder_y
      - .offset:         198
        .size:           2
        .value_kind:     hidden_remainder_z
      - .offset:         216
        .size:           8
        .value_kind:     hidden_global_offset_x
      - .offset:         224
        .size:           8
        .value_kind:     hidden_global_offset_y
      - .offset:         232
        .size:           8
        .value_kind:     hidden_global_offset_z
      - .offset:         240
        .size:           2
        .value_kind:     hidden_grid_dims
      - .offset:         264
        .size:           8
        .value_kind:     hidden_multigrid_sync_arg
      - .offset:         296
        .size:           4
        .value_kind:     hidden_dynamic_lds_size
    .group_segment_fixed_size: 0
    .kernarg_segment_align: 8
    .kernarg_segment_size: 432
    .language:       OpenCL C
    .language_version:
      - 2
      - 0
    .max_flat_workgroup_size: 512
    .name:           _ZN2mk3fwdENS_4ArgsE
    .private_segment_fixed_size: 0
    .sgpr_count:     108
    .sgpr_spill_count: 184
    .symbol:         _ZN2mk3fwdENS_4ArgsE.kd
    .uniform_work_group_size: 1
    .uses_dynamic_stack: false
    .vgpr_count:     256
    .vgpr_spill_count: 0
    .wavefront_size: 64
